# MLA: extend the unmasked fast loop by two tiles per query block (tiles 4qb-2, 4qb-1 need no mask)
# speedup vs baseline: 1.0120x; 1.0120x over previous
.LBB0_1334:
	s_lshl_b32 s16, s14, 2
	s_cmp_lt_i32 s14, 1
	s_cselect_b64 s[10:11], -1, 0
	v_add_u32_e32 v217, v17, v16
	s_and_b64 vcc, exec, s[10:11]
	s_barrier
	s_cbranch_vccnz .LBB0_1362
	v_add_u32_e32 v226, v221, v220
	v_mul_lo_u32 v1, v226, 12
	v_sub_u32_e32 v1, v218, v1
	v_lshlrev_b32_e32 v2, 3, v1
	v_ashrrev_i32_e32 v3, 31, v2
	v_add_u32_e32 v227, v224, v223
	v_lshl_add_u64 v[204:205], v[2:3], 1, s[2:3]
	v_mul_lo_u32 v2, v227, 12
	v_sub_u32_e32 v4, v222, v2
	v_lshlrev_b32_e32 v2, 3, v4
	v_ashrrev_i32_e32 v3, 31, v2
	v_lshlrev_b32_e32 v17, 4, v1
	v_mul_lo_u32 v1, v227, s92
	v_lshl_add_u64 v[206:207], v[2:3], 1, s[2:3]
	v_mul_lo_u32 v2, v226, s92
	v_add_u32_e32 v18, 0, v1
	v_lshlrev_b32_e32 v19, 4, v4
	v_mov_b32_e32 v14, v0
	v_mov_b32_e32 v15, v0
	v_add_u32_e32 v16, 0, v2
	v_mov_b32_e32 v1, v0
	v_mov_b32_e32 v2, v0
	v_mov_b32_e32 v3, v0
	v_mov_b32_e32 v4, v0
	v_mov_b32_e32 v5, v0
	v_mov_b32_e32 v6, v0
	v_mov_b32_e32 v7, v0
	v_mov_b32_e32 v8, v0
	v_mov_b32_e32 v9, v0
	v_mov_b32_e32 v10, v0
	v_mov_b32_e32 v11, v0
	v_mov_b32_e32 v12, v0
	v_mov_b32_e32 v13, v0
	v_add_u32_e32 v229, v18, v19
	v_mov_b64_e32 v[32:33], v[14:15]
	v_mov_b32_e32 v171, 0
	v_add_u32_e32 v228, v16, v17
	v_mov_b64_e32 v[30:31], v[12:13]
	v_mov_b64_e32 v[28:29], v[10:11]
	v_mov_b64_e32 v[26:27], v[8:9]
	v_mov_b64_e32 v[24:25], v[6:7]
	v_mov_b64_e32 v[22:23], v[4:5]
	v_mov_b64_e32 v[20:21], v[2:3]
	v_mov_b64_e32 v[18:19], v[0:1]
	v_mov_b64_e32 v[16:17], v[14:15]
	s_add_i32 s17, s16, 1
	s_mov_b32 s18, 0
	s_mov_b64 s[42:43], -1
	s_movk_i32 s19, 0x100
	v_mov_b64_e32 v[14:15], v[12:13]
	v_mov_b64_e32 v[12:13], v[10:11]
	v_mov_b64_e32 v[10:11], v[8:9]
	v_mov_b64_e32 v[8:9], v[6:7]
	v_mov_b64_e32 v[6:7], v[4:5]
	v_mov_b64_e32 v[4:5], v[2:3]
	v_mov_b64_e32 v[2:3], v[0:1]
	v_mov_b32_e32 v202, v171
